# sample-MLA value up-projection: W_uv^T fragment loads double-buffered one round ahead
# speedup vs baseline: 1.0225x; 1.0063x over previous
.LBB0_976:
	s_cmpk_lt_u32 s37, 0x80
	s_cbranch_scc0 .LBB0_933
	s_lshl_b32 s6, s36, 15
	s_add_u32 s10, s34, s6
	s_addc_u32 s11, s35, 0
	s_lshl_b64 s[6:7], s[8:9], 11
	s_add_u32 s6, s88, s6
	s_addc_u32 s7, s89, s7
	s_lshl_b32 s8, s36, 7
	s_add_u32 s6, s6, s8
	v_div_scale_f32 v131, s[8:9], v130, v130, 1.0
	v_rcp_f32_e32 v132, v131
	v_lshlrev_b32_e32 v198, 9, v220
	s_mov_b64 s[8:9], 0x740000
	s_addc_u32 s7, s7, 0
	v_fma_f32 v133, -v131, v132, 1.0
	v_fmac_f32_e32 v132, v133, v132
	v_div_scale_f32 v133, vcc, 1.0, v130, 1.0
	v_mul_f32_e32 v134, v133, v132
	v_fma_f32 v135, -v131, v134, v133
	v_fmac_f32_e32 v134, v135, v132
	v_fma_f32 v131, -v131, v134, v133
	v_div_fmas_f32 v131, v131, v132, v134
	v_div_fixup_f32 v164, v131, v130, 1.0
	v_lshl_add_u64 v[130:131], s[10:11], 0, v[198:199]
	v_lshlrev_b32_e32 v198, 1, v201
	v_pk_mul_f32 v[114:115], v[114:115], v[164:165] op_sel_hi:[1,0]
	v_lshl_add_u64 v[134:135], v[130:131], 0, v[198:199]
	v_cvt_pk_bf16_f32 v130, v114, v115
	v_pk_mul_f32 v[114:115], v[116:117], v[164:165] op_sel_hi:[1,0]
	v_lshl_add_u64 v[162:163], v[134:135], 0, s[8:9]
	v_cvt_pk_bf16_f32 v131, v114, v115
	v_pk_mul_f32 v[114:115], v[118:119], v[164:165] op_sel_hi:[1,0]
	s_mov_b32 s8, 0x740000
	v_cvt_pk_bf16_f32 v132, v114, v115
	v_pk_mul_f32 v[114:115], v[120:121], v[164:165] op_sel_hi:[1,0]
	v_pk_mul_f32 v[120:121], v[128:129], v[164:165] op_sel_hi:[1,0]
	v_cvt_pk_bf16_f32 v133, v114, v115
	v_add_co_u32_e32 v114, vcc, s8, v134
	s_mov_b32 s8, 0x744000
	s_nop 0
	v_addc_co_u32_e32 v115, vcc, 0, v135, vcc
	v_add_co_u32_e32 v114, vcc, s8, v134
	v_pk_mul_f32 v[98:99], v[98:99], v[164:165] op_sel_hi:[1,0]
	s_nop 0
	v_addc_co_u32_e32 v115, vcc, 0, v135, vcc
	global_load_dwordx2 v[232:233], v[162:163], off
	global_load_dwordx2 v[234:235], v[162:163], off offset:16
	global_load_dwordx2 v[236:237], v[114:115], off
	global_load_dwordx2 v[238:239], v[114:115], off offset:16
	global_load_dwordx2 v[240:241], v[162:163], off offset:32
	global_load_dwordx2 v[242:243], v[162:163], off offset:48
	global_load_dwordx2 v[246:247], v[114:115], off offset:32
	global_load_dwordx2 v[248:249], v[114:115], off offset:48
	v_pk_mul_f32 v[100:101], v[100:101], v[164:165] op_sel_hi:[1,0]
	v_cvt_pk_bf16_f32 v98, v98, v99
	v_cvt_pk_bf16_f32 v99, v100, v101
	v_pk_mul_f32 v[100:101], v[102:103], v[164:165] op_sel_hi:[1,0]
	v_pk_mul_f32 v[102:103], v[104:105], v[164:165] op_sel_hi:[1,0]
	v_cvt_pk_bf16_f32 v100, v100, v101
	v_cvt_pk_bf16_f32 v101, v102, v103
	v_pk_mul_f32 v[82:83], v[82:83], v[164:165] op_sel_hi:[1,0]
	v_pk_mul_f32 v[84:85], v[84:85], v[164:165] op_sel_hi:[1,0]
	v_cvt_pk_bf16_f32 v82, v82, v83
	v_cvt_pk_bf16_f32 v83, v84, v85
	v_pk_mul_f32 v[84:85], v[86:87], v[164:165] op_sel_hi:[1,0]
	v_pk_mul_f32 v[86:87], v[88:89], v[164:165] op_sel_hi:[1,0]
	v_cvt_pk_bf16_f32 v84, v84, v85
	v_cvt_pk_bf16_f32 v85, v86, v87
	v_pk_mul_f32 v[66:67], v[66:67], v[164:165] op_sel_hi:[1,0]
	v_pk_mul_f32 v[68:69], v[68:69], v[164:165] op_sel_hi:[1,0]
	v_cvt_pk_bf16_f32 v66, v66, v67
	v_cvt_pk_bf16_f32 v67, v68, v69
	v_pk_mul_f32 v[68:69], v[70:71], v[164:165] op_sel_hi:[1,0]
	v_pk_mul_f32 v[70:71], v[72:73], v[164:165] op_sel_hi:[1,0]
	v_cvt_pk_bf16_f32 v68, v68, v69
	v_cvt_pk_bf16_f32 v69, v70, v71
	v_pk_mul_f32 v[50:51], v[50:51], v[164:165] op_sel_hi:[1,0]
	v_pk_mul_f32 v[52:53], v[52:53], v[164:165] op_sel_hi:[1,0]
	v_cvt_pk_bf16_f32 v50, v50, v51
	v_cvt_pk_bf16_f32 v51, v52, v53
	v_pk_mul_f32 v[52:53], v[54:55], v[164:165] op_sel_hi:[1,0]
	v_pk_mul_f32 v[54:55], v[56:57], v[164:165] op_sel_hi:[1,0]
	v_cvt_pk_bf16_f32 v52, v52, v53
	v_cvt_pk_bf16_f32 v53, v54, v55
	v_pk_mul_f32 v[34:35], v[34:35], v[164:165] op_sel_hi:[1,0]
	v_pk_mul_f32 v[36:37], v[36:37], v[164:165] op_sel_hi:[1,0]
	v_cvt_pk_bf16_f32 v34, v34, v35
	v_cvt_pk_bf16_f32 v35, v36, v37
	v_pk_mul_f32 v[36:37], v[38:39], v[164:165] op_sel_hi:[1,0]
	v_pk_mul_f32 v[38:39], v[40:41], v[164:165] op_sel_hi:[1,0]
	v_cvt_pk_bf16_f32 v36, v36, v37
	v_cvt_pk_bf16_f32 v37, v38, v39
	v_pk_mul_f32 v[18:19], v[18:19], v[164:165] op_sel_hi:[1,0]
	v_pk_mul_f32 v[20:21], v[20:21], v[164:165] op_sel_hi:[1,0]
	v_cvt_pk_bf16_f32 v18, v18, v19
	v_cvt_pk_bf16_f32 v19, v20, v21
	v_pk_mul_f32 v[20:21], v[22:23], v[164:165] op_sel_hi:[1,0]
	v_pk_mul_f32 v[22:23], v[24:25], v[164:165] op_sel_hi:[1,0]
	v_cvt_pk_bf16_f32 v20, v20, v21
	v_cvt_pk_bf16_f32 v21, v22, v23
	v_pk_mul_f32 v[2:3], v[2:3], v[164:165] op_sel_hi:[1,0]
	v_pk_mul_f32 v[4:5], v[4:5], v[164:165] op_sel_hi:[1,0]
	v_cvt_pk_bf16_f32 v2, v2, v3
	v_cvt_pk_bf16_f32 v3, v4, v5
	v_pk_mul_f32 v[4:5], v[6:7], v[164:165] op_sel_hi:[1,0]
	v_pk_mul_f32 v[6:7], v[8:9], v[164:165] op_sel_hi:[1,0]
	v_cvt_pk_bf16_f32 v4, v4, v5
	s_waitcnt vmcnt(4)
	v_mfma_f32_32x32x16_bf16 v[146:161], v[232:235], v[130:133], 0
	v_mul_f32_e64 v116, v122, v164
	v_mul_f32_e64 v117, v123, v164
	v_mul_f32_e64 v118, v124, v164
	v_mul_f32_e64 v119, v125, v164
	v_cvt_pk_bf16_f32 v116, v116, v117
	v_cvt_pk_bf16_f32 v117, v118, v119
	v_pk_mul_f32 v[118:119], v[126:127], v[164:165] op_sel_hi:[1,0]
	v_cvt_pk_bf16_f32 v5, v6, v7
	v_cvt_pk_bf16_f32 v118, v118, v119
	v_cvt_pk_bf16_f32 v119, v120, v121
	v_mfma_f32_32x32x16_bf16 v[130:145], v[236:239], v[130:133], 0
	global_load_dwordx2 v[232:233], v[162:163], off offset:64
	global_load_dwordx2 v[234:235], v[162:163], off offset:80
	global_load_dwordx2 v[236:237], v[114:115], off offset:64
	global_load_dwordx2 v[238:239], v[114:115], off offset:80
	s_waitcnt vmcnt(4)
	v_mfma_f32_32x32x16_bf16 v[146:161], v[240:243], v[116:119], v[146:161]
	v_mfma_f32_32x32x16_bf16 v[130:145], v[246:249], v[116:119], v[130:145]
	global_load_dwordx2 v[240:241], v[162:163], off offset:96
	global_load_dwordx2 v[242:243], v[162:163], off offset:112
	global_load_dwordx2 v[246:247], v[114:115], off offset:96
	global_load_dwordx2 v[248:249], v[114:115], off offset:112
	s_waitcnt vmcnt(4)
	v_mfma_f32_32x32x16_bf16 v[146:161], v[232:235], v[98:101], v[146:161]
	v_mul_f32_e64 v102, v112, v164
	v_mul_f32_e64 v103, v113, v164
	v_mfma_f32_32x32x16_bf16 v[130:145], v[236:239], v[98:101], v[130:145]
	global_load_dwordx2 v[232:233], v[162:163], off offset:128
	global_load_dwordx2 v[234:235], v[162:163], off offset:144
	global_load_dwordx2 v[236:237], v[114:115], off offset:128
	global_load_dwordx2 v[238:239], v[114:115], off offset:144
	v_mul_f32_e64 v98, v106, v164
	v_mul_f32_e64 v99, v107, v164
	v_mul_f32_e64 v100, v108, v164
	v_mul_f32_e64 v101, v109, v164
	v_cvt_pk_bf16_f32 v98, v98, v99
	v_cvt_pk_bf16_f32 v99, v100, v101
	v_pk_mul_f32 v[100:101], v[110:111], v[164:165] op_sel_hi:[1,0]
	s_nop 0
	v_cvt_pk_bf16_f32 v100, v100, v101
	v_cvt_pk_bf16_f32 v101, v102, v103
	s_waitcnt vmcnt(4)
	v_mfma_f32_32x32x16_bf16 v[146:161], v[240:243], v[98:101], v[146:161]
	v_mfma_f32_32x32x16_bf16 v[130:145], v[246:249], v[98:101], v[130:145]
	global_load_dwordx2 v[240:241], v[162:163], off offset:160
	global_load_dwordx2 v[242:243], v[162:163], off offset:176
	global_load_dwordx2 v[246:247], v[114:115], off offset:160
	global_load_dwordx2 v[248:249], v[114:115], off offset:176
	s_waitcnt vmcnt(4)
	v_mfma_f32_32x32x16_bf16 v[146:161], v[232:235], v[82:85], v[146:161]
	v_mul_f32_e64 v86, v96, v164
	v_mul_f32_e64 v87, v97, v164
	v_mfma_f32_32x32x16_bf16 v[130:145], v[236:239], v[82:85], v[130:145]
	global_load_dwordx2 v[232:233], v[162:163], off offset:192
	global_load_dwordx2 v[234:235], v[162:163], off offset:208
	global_load_dwordx2 v[236:237], v[114:115], off offset:192
	global_load_dwordx2 v[238:239], v[114:115], off offset:208
	v_mul_f32_e64 v82, v90, v164
	v_mul_f32_e64 v83, v91, v164
	v_mul_f32_e64 v84, v92, v164
	v_mul_f32_e64 v85, v93, v164
	v_cvt_pk_bf16_f32 v82, v82, v83
	v_cvt_pk_bf16_f32 v83, v84, v85
	v_pk_mul_f32 v[84:85], v[94:95], v[164:165] op_sel_hi:[1,0]
	s_nop 0
	v_cvt_pk_bf16_f32 v84, v84, v85
	v_cvt_pk_bf16_f32 v85, v86, v87
	s_waitcnt vmcnt(4)
	v_mfma_f32_32x32x16_bf16 v[146:161], v[240:243], v[82:85], v[146:161]
	v_mfma_f32_32x32x16_bf16 v[130:145], v[246:249], v[82:85], v[130:145]
	global_load_dwordx2 v[240:241], v[162:163], off offset:224
	global_load_dwordx2 v[242:243], v[162:163], off offset:240
	global_load_dwordx2 v[246:247], v[114:115], off offset:224
	global_load_dwordx2 v[248:249], v[114:115], off offset:240
	s_waitcnt vmcnt(4)
	v_mfma_f32_32x32x16_bf16 v[146:161], v[232:235], v[66:69], v[146:161]
	v_mul_f32_e64 v70, v80, v164
	v_mul_f32_e64 v71, v81, v164
	v_mfma_f32_32x32x16_bf16 v[130:145], v[236:239], v[66:69], v[130:145]
	global_load_dwordx2 v[232:233], v[162:163], off offset:256
	global_load_dwordx2 v[234:235], v[162:163], off offset:272
	global_load_dwordx2 v[236:237], v[114:115], off offset:256
	global_load_dwordx2 v[238:239], v[114:115], off offset:272
	v_mul_f32_e64 v66, v74, v164
	v_mul_f32_e64 v67, v75, v164
	v_mul_f32_e64 v68, v76, v164
	v_mul_f32_e64 v69, v77, v164
	v_cvt_pk_bf16_f32 v66, v66, v67
	v_cvt_pk_bf16_f32 v67, v68, v69
	v_pk_mul_f32 v[68:69], v[78:79], v[164:165] op_sel_hi:[1,0]
	s_nop 0
	v_cvt_pk_bf16_f32 v68, v68, v69
	v_cvt_pk_bf16_f32 v69, v70, v71
	s_waitcnt vmcnt(4)
	v_mfma_f32_32x32x16_bf16 v[146:161], v[240:243], v[66:69], v[146:161]
	v_mfma_f32_32x32x16_bf16 v[130:145], v[246:249], v[66:69], v[130:145]
	global_load_dwordx2 v[240:241], v[162:163], off offset:288
	global_load_dwordx2 v[242:243], v[162:163], off offset:304
	global_load_dwordx2 v[246:247], v[114:115], off offset:288
	global_load_dwordx2 v[248:249], v[114:115], off offset:304
	s_waitcnt vmcnt(4)
	v_mfma_f32_32x32x16_bf16 v[146:161], v[232:235], v[50:53], v[146:161]
	v_mul_f32_e64 v54, v64, v164
	v_mul_f32_e64 v55, v65, v164
	v_mfma_f32_32x32x16_bf16 v[130:145], v[236:239], v[50:53], v[130:145]
	global_load_dwordx2 v[232:233], v[162:163], off offset:320
	global_load_dwordx2 v[234:235], v[162:163], off offset:336
	global_load_dwordx2 v[236:237], v[114:115], off offset:320
	global_load_dwordx2 v[238:239], v[114:115], off offset:336
	v_mul_f32_e64 v50, v58, v164
	v_mul_f32_e64 v51, v59, v164
	v_mul_f32_e64 v52, v60, v164
	v_mul_f32_e64 v53, v61, v164
	v_cvt_pk_bf16_f32 v50, v50, v51
	v_cvt_pk_bf16_f32 v51, v52, v53
	v_pk_mul_f32 v[52:53], v[62:63], v[164:165] op_sel_hi:[1,0]
	s_nop 0
	v_cvt_pk_bf16_f32 v52, v52, v53
	v_cvt_pk_bf16_f32 v53, v54, v55
	s_waitcnt vmcnt(4)
	v_mfma_f32_32x32x16_bf16 v[146:161], v[240:243], v[50:53], v[146:161]
	v_mfma_f32_32x32x16_bf16 v[130:145], v[246:249], v[50:53], v[130:145]
	global_load_dwordx2 v[240:241], v[162:163], off offset:352
	global_load_dwordx2 v[242:243], v[162:163], off offset:368
	global_load_dwordx2 v[246:247], v[114:115], off offset:352
	global_load_dwordx2 v[248:249], v[114:115], off offset:368
	s_waitcnt vmcnt(4)
	v_mfma_f32_32x32x16_bf16 v[146:161], v[232:235], v[34:37], v[146:161]
	v_mul_f32_e64 v38, v48, v164
	v_mul_f32_e64 v39, v49, v164
	v_mfma_f32_32x32x16_bf16 v[130:145], v[236:239], v[34:37], v[130:145]
	global_load_dwordx2 v[232:233], v[162:163], off offset:384
	global_load_dwordx2 v[234:235], v[162:163], off offset:400
	global_load_dwordx2 v[236:237], v[114:115], off offset:384
	global_load_dwordx2 v[238:239], v[114:115], off offset:400
	v_mul_f32_e64 v34, v42, v164
	v_mul_f32_e64 v35, v43, v164
	v_mul_f32_e64 v36, v44, v164
	v_mul_f32_e64 v37, v45, v164
	v_cvt_pk_bf16_f32 v34, v34, v35
	v_cvt_pk_bf16_f32 v35, v36, v37
	v_pk_mul_f32 v[36:37], v[46:47], v[164:165] op_sel_hi:[1,0]
	s_nop 0
	v_cvt_pk_bf16_f32 v36, v36, v37
	v_cvt_pk_bf16_f32 v37, v38, v39
	s_waitcnt vmcnt(4)
	v_mfma_f32_32x32x16_bf16 v[146:161], v[240:243], v[34:37], v[146:161]
	v_mfma_f32_32x32x16_bf16 v[130:145], v[246:249], v[34:37], v[130:145]
	global_load_dwordx2 v[240:241], v[162:163], off offset:416
	global_load_dwordx2 v[242:243], v[162:163], off offset:432
	global_load_dwordx2 v[246:247], v[114:115], off offset:416
	global_load_dwordx2 v[248:249], v[114:115], off offset:432
	s_waitcnt vmcnt(4)
	v_mfma_f32_32x32x16_bf16 v[146:161], v[232:235], v[18:21], v[146:161]
	v_mul_f32_e64 v22, v32, v164
	v_mul_f32_e64 v23, v33, v164
	v_mfma_f32_32x32x16_bf16 v[130:145], v[236:239], v[18:21], v[130:145]
	global_load_dwordx2 v[232:233], v[162:163], off offset:448
	global_load_dwordx2 v[234:235], v[162:163], off offset:464
	global_load_dwordx2 v[236:237], v[114:115], off offset:448
	global_load_dwordx2 v[238:239], v[114:115], off offset:464
	v_mul_f32_e64 v18, v26, v164
	v_mul_f32_e64 v19, v27, v164
	v_mul_f32_e64 v20, v28, v164
	v_mul_f32_e64 v21, v29, v164
	v_cvt_pk_bf16_f32 v18, v18, v19
	v_cvt_pk_bf16_f32 v19, v20, v21
	v_pk_mul_f32 v[20:21], v[30:31], v[164:165] op_sel_hi:[1,0]
	s_nop 0
	v_cvt_pk_bf16_f32 v20, v20, v21
	v_cvt_pk_bf16_f32 v21, v22, v23
	s_waitcnt vmcnt(4)
	v_mfma_f32_32x32x16_bf16 v[146:161], v[240:243], v[18:21], v[146:161]
	v_mfma_f32_32x32x16_bf16 v[130:145], v[246:249], v[18:21], v[130:145]
	global_load_dwordx2 v[240:241], v[162:163], off offset:480
	global_load_dwordx2 v[242:243], v[162:163], off offset:496
	global_load_dwordx2 v[246:247], v[114:115], off offset:480
	global_load_dwordx2 v[248:249], v[114:115], off offset:496
	s_waitcnt vmcnt(4)
	v_mfma_f32_32x32x16_bf16 v[146:161], v[232:235], v[2:5], v[146:161]
	v_mul_f32_e64 v6, v16, v164
	v_mul_f32_e64 v7, v17, v164
	v_mfma_f32_32x32x16_bf16 v[130:145], v[236:239], v[2:5], v[130:145]
	v_mul_f32_e64 v2, v10, v164
	v_mul_f32_e64 v3, v11, v164
	v_mul_f32_e64 v4, v12, v164
	v_mul_f32_e64 v5, v13, v164
	v_cvt_pk_bf16_f32 v2, v2, v3
	v_cvt_pk_bf16_f32 v3, v4, v5
	v_pk_mul_f32 v[4:5], v[14:15], v[164:165] op_sel_hi:[1,0]
	s_nop 0
	v_cvt_pk_bf16_f32 v4, v4, v5
	v_cvt_pk_bf16_f32 v5, v6, v7
	s_waitcnt vmcnt(0)
	v_mfma_f32_32x32x16_bf16 v[146:161], v[240:243], v[2:5], v[146:161]
	v_mfma_f32_32x32x16_bf16 v[130:145], v[246:249], v[2:5], v[130:145]
	v_lshlrev_b32_e32 v2, 11, v1
	v_mov_b32_e32 v3, v199
	v_lshl_add_u64 v[2:3], s[6:7], 0, v[2:3]
	v_lshl_add_u64 v[2:3], v[2:3], 0, v[198:199]
	s_nop 5
	v_cvt_pk_bf16_f32 v4, v146, v147
	v_cvt_pk_bf16_f32 v5, v148, v149
	global_store_dwordx2 v[2:3], v[4:5], off offset:1024
	v_cvt_pk_bf16_f32 v4, v130, v131
	v_cvt_pk_bf16_f32 v5, v132, v133
	global_store_dwordx2 v[2:3], v[4:5], off offset:1088
	v_cvt_pk_bf16_f32 v4, v150, v151
	v_cvt_pk_bf16_f32 v5, v152, v153
	global_store_dwordx2 v[2:3], v[4:5], off offset:1040
	v_cvt_pk_bf16_f32 v4, v134, v135
	v_cvt_pk_bf16_f32 v5, v136, v137
	global_store_dwordx2 v[2:3], v[4:5], off offset:1104
	v_cvt_pk_bf16_f32 v4, v154, v155
	v_cvt_pk_bf16_f32 v5, v156, v157
	global_store_dwordx2 v[2:3], v[4:5], off offset:1056
	v_cvt_pk_bf16_f32 v4, v138, v139
	v_cvt_pk_bf16_f32 v5, v140, v141
	global_store_dwordx2 v[2:3], v[4:5], off offset:1120
	v_cvt_pk_bf16_f32 v4, v158, v159
	v_cvt_pk_bf16_f32 v5, v160, v161
	global_store_dwordx2 v[2:3], v[4:5], off offset:1072
	v_cvt_pk_bf16_f32 v4, v142, v143
	v_cvt_pk_bf16_f32 v5, v144, v145
	global_store_dwordx2 v[2:3], v[4:5], off offset:1136
	s_branch .LBB0_933
